# v26 minus 12 redundant s_nop 0 between cvt_pk and the V fragment reads in the four diff-attn PV blocks
# baseline (speedup 1.0000x reference)
.LBB0_44:
.LBB0_45:
	v_add3_u32 v190, s26, v178, v177
	ds_read_b64_tr_b16 v[240:241], v190 offset:9216
	ds_read_b64_tr_b16 v[242:243], v190 offset:11776
	ds_read_b64_tr_b16 v[244:245], v190 offset:9280
	ds_read_b64_tr_b16 v[246:247], v190 offset:11840
	ds_read_b64_tr_b16 v[214:215], v190 offset:9344
	ds_read_b64_tr_b16 v[216:217], v190 offset:11904
	v_exp_f32_e32 v82, v82
	v_exp_f32_e32 v83, v83
	v_exp_f32_e32 v84, v84
	v_exp_f32_e32 v85, v85
	v_exp_f32_e32 v86, v86
	v_exp_f32_e32 v87, v87
	v_exp_f32_e32 v88, v88
	v_exp_f32_e32 v89, v89
	v_add_f32_e32 v238, v82, v83
	v_add_f32_e32 v239, v239, v84
	v_add_f32_e32 v238, v238, v85
	v_cvt_pk_bf16_f32 v82, v82, v83
	v_cvt_pk_bf16_f32 v83, v84, v85
	v_cvt_pk_bf16_f32 v84, v86, v87
	v_cvt_pk_bf16_f32 v85, v88, v89
	s_setprio 1
	s_waitcnt lgkmcnt(4)
	v_mfma_f32_32x32x16_bf16 v[2:17], v[82:85], v[240:243], v[2:17]
	v_add_f32_e32 v239, v239, v86
	v_add_f32_e32 v238, v238, v87
	v_add_f32_e32 v239, v239, v88
	v_add_f32_e32 v238, v238, v89
	v_exp_f32_e32 v90, v90
	v_exp_f32_e32 v91, v91
	ds_read_b64_tr_b16 v[240:241], v190 offset:9408
	ds_read_b64_tr_b16 v[242:243], v190 offset:11968
	s_waitcnt lgkmcnt(4)
	v_mfma_f32_32x32x16_bf16 v[50:65], v[82:85], v[244:247], v[50:65]
	v_exp_f32_e32 v92, v92
	v_exp_f32_e32 v93, v93
	v_exp_f32_e32 v94, v94
	ds_read_b64_tr_b16 v[244:245], v190 offset:14336
	ds_read_b64_tr_b16 v[246:247], v190 offset:16896
	s_waitcnt lgkmcnt(4)
	v_mfma_f32_32x32x16_bf16 v[34:49], v[82:85], v[214:217], v[34:49]
	v_exp_f32_e32 v95, v95
	v_exp_f32_e32 v96, v96
	v_exp_f32_e32 v97, v97
	v_add_f32_e32 v239, v239, v90
	ds_read_b64_tr_b16 v[214:215], v190 offset:14400
	ds_read_b64_tr_b16 v[216:217], v190 offset:16960
	s_waitcnt lgkmcnt(4)
	v_mfma_f32_32x32x16_bf16 v[18:33], v[82:85], v[240:243], v[18:33]
	v_add_f32_e32 v238, v238, v91
	v_add_f32_e32 v239, v239, v92
	v_add_f32_e32 v238, v238, v93
	v_cvt_pk_bf16_f32 v90, v90, v91
	v_cvt_pk_bf16_f32 v91, v92, v93
	v_cvt_pk_bf16_f32 v92, v94, v95
	v_cvt_pk_bf16_f32 v93, v96, v97
	ds_read_b64_tr_b16 v[240:241], v190 offset:14464
	ds_read_b64_tr_b16 v[242:243], v190 offset:17024
	s_waitcnt lgkmcnt(4)
	v_mfma_f32_32x32x16_bf16 v[2:17], v[90:93], v[244:247], v[2:17]
	v_add_f32_e32 v239, v239, v94
	v_add_f32_e32 v238, v238, v95
	v_add_f32_e32 v239, v239, v96
	v_add_f32_e32 v238, v238, v97
	v_exp_f32_e32 v98, v98
	v_exp_f32_e32 v99, v99
	ds_read_b64_tr_b16 v[244:245], v190 offset:14528
	ds_read_b64_tr_b16 v[246:247], v190 offset:17088
	s_waitcnt lgkmcnt(4)
	v_mfma_f32_32x32x16_bf16 v[50:65], v[90:93], v[214:217], v[50:65]
	v_exp_f32_e32 v100, v100
	v_exp_f32_e32 v101, v101
	v_exp_f32_e32 v102, v102
	ds_read_b64_tr_b16 v[214:215], v190 offset:19456
	ds_read_b64_tr_b16 v[216:217], v190 offset:22016
	s_waitcnt lgkmcnt(4)
	v_mfma_f32_32x32x16_bf16 v[34:49], v[90:93], v[240:243], v[34:49]
	v_exp_f32_e32 v103, v103
	v_exp_f32_e32 v104, v104
	v_exp_f32_e32 v105, v105
	v_add_f32_e32 v239, v239, v98
	ds_read_b64_tr_b16 v[240:241], v190 offset:19520
	ds_read_b64_tr_b16 v[242:243], v190 offset:22080
	s_waitcnt lgkmcnt(4)
	v_mfma_f32_32x32x16_bf16 v[18:33], v[90:93], v[244:247], v[18:33]
	v_add_f32_e32 v238, v238, v99
	v_add_f32_e32 v239, v239, v100
	v_add_f32_e32 v238, v238, v101
	v_cvt_pk_bf16_f32 v98, v98, v99
	v_cvt_pk_bf16_f32 v99, v100, v101
	v_cvt_pk_bf16_f32 v100, v102, v103
	v_cvt_pk_bf16_f32 v101, v104, v105
	ds_read_b64_tr_b16 v[244:245], v190 offset:19584
	ds_read_b64_tr_b16 v[246:247], v190 offset:22144
	s_waitcnt lgkmcnt(4)
	v_mfma_f32_32x32x16_bf16 v[2:17], v[98:101], v[214:217], v[2:17]
	v_add_f32_e32 v239, v239, v102
	v_add_f32_e32 v238, v238, v103
	v_add_f32_e32 v239, v239, v104
	v_add_f32_e32 v238, v238, v105
	v_exp_f32_e32 v106, v106
	v_exp_f32_e32 v107, v107
	ds_read_b64_tr_b16 v[214:215], v190 offset:19648
	ds_read_b64_tr_b16 v[216:217], v190 offset:22208
	s_waitcnt lgkmcnt(4)
	v_mfma_f32_32x32x16_bf16 v[50:65], v[98:101], v[240:243], v[50:65]
	v_exp_f32_e32 v108, v108
	v_exp_f32_e32 v109, v109
	v_exp_f32_e32 v110, v110
	ds_read_b64_tr_b16 v[240:241], v190 offset:24576
	ds_read_b64_tr_b16 v[242:243], v190 offset:27136
	s_waitcnt lgkmcnt(4)
	v_mfma_f32_32x32x16_bf16 v[34:49], v[98:101], v[244:247], v[34:49]
	v_exp_f32_e32 v111, v111
	v_exp_f32_e32 v112, v112
	v_exp_f32_e32 v113, v113
	v_add_f32_e32 v239, v239, v106
	ds_read_b64_tr_b16 v[244:245], v190 offset:24640
	ds_read_b64_tr_b16 v[246:247], v190 offset:27200
	s_waitcnt lgkmcnt(4)
	v_mfma_f32_32x32x16_bf16 v[18:33], v[98:101], v[214:217], v[18:33]
	v_add_f32_e32 v238, v238, v107
	v_add_f32_e32 v239, v239, v108
	v_add_f32_e32 v238, v238, v109
	v_cvt_pk_bf16_f32 v106, v106, v107
	v_cvt_pk_bf16_f32 v107, v108, v109
	v_cvt_pk_bf16_f32 v108, v110, v111
	v_cvt_pk_bf16_f32 v109, v112, v113
	ds_read_b64_tr_b16 v[214:215], v190 offset:24704
	ds_read_b64_tr_b16 v[216:217], v190 offset:27264
	s_waitcnt lgkmcnt(4)
	v_mfma_f32_32x32x16_bf16 v[2:17], v[106:109], v[240:243], v[2:17]
	v_add_f32_e32 v239, v239, v110
	v_add_f32_e32 v238, v238, v111
	v_add_f32_e32 v239, v239, v112
	v_add_f32_e32 v238, v238, v113
	v_add_f32_e32 v239, v239, v238
	ds_read_b64_tr_b16 v[240:241], v190 offset:24768
	ds_read_b64_tr_b16 v[242:243], v190 offset:27328
	s_waitcnt lgkmcnt(4)
	v_mfma_f32_32x32x16_bf16 v[50:65], v[106:109], v[244:247], v[50:65]
	s_waitcnt lgkmcnt(2)
	v_mfma_f32_32x32x16_bf16 v[34:49], v[106:109], v[214:217], v[34:49]
	s_waitcnt lgkmcnt(0)
	v_mfma_f32_32x32x16_bf16 v[18:33], v[106:109], v[240:243], v[18:33]
	s_setprio 0
	s_movk_i32 s77, 0x110

.LBB0_59:
.LBB0_60:
	v_add3_u32 v153, s26, v178, v177
	ds_read_b64_tr_b16 v[154:155], v153 offset:9216
	ds_read_b64_tr_b16 v[156:157], v153 offset:11776
	ds_read_b64_tr_b16 v[190:191], v153 offset:9280
	ds_read_b64_tr_b16 v[192:193], v153 offset:11840
	ds_read_b64_tr_b16 v[214:215], v153 offset:9344
	ds_read_b64_tr_b16 v[216:217], v153 offset:11904
	ds_read_b64_tr_b16 v[234:235], v153 offset:9408
	ds_read_b64_tr_b16 v[236:237], v153 offset:11968
	v_exp_f32_e32 v82, v82
	v_exp_f32_e32 v83, v83
	v_exp_f32_e32 v84, v84
	v_exp_f32_e32 v85, v85
	v_exp_f32_e32 v86, v86
	v_exp_f32_e32 v87, v87
	v_exp_f32_e32 v88, v88
	v_exp_f32_e32 v89, v89
	v_add_f32_e32 v239, v82, v83
	v_add_f32_e32 v238, v238, v84
	v_add_f32_e32 v239, v239, v85
	v_cvt_pk_bf16_f32 v82, v82, v83
	v_cvt_pk_bf16_f32 v83, v84, v85
	v_cvt_pk_bf16_f32 v84, v86, v87
	v_cvt_pk_bf16_f32 v85, v88, v89
	s_setprio 1
	s_waitcnt lgkmcnt(6)
	v_mfma_f32_32x32x16_bf16 v[2:17], v[82:85], v[154:157], v[2:17]
	v_add_f32_e32 v238, v238, v86
	v_add_f32_e32 v239, v239, v87
	v_add_f32_e32 v238, v238, v88
	v_add_f32_e32 v239, v239, v89
	v_exp_f32_e32 v90, v90
	v_exp_f32_e32 v91, v91
	ds_read_b64_tr_b16 v[154:155], v153 offset:14336
	ds_read_b64_tr_b16 v[156:157], v153 offset:16896
	s_waitcnt lgkmcnt(6)
	v_mfma_f32_32x32x16_bf16 v[50:65], v[82:85], v[190:193], v[50:65]
	v_exp_f32_e32 v92, v92
	v_exp_f32_e32 v93, v93
	v_exp_f32_e32 v94, v94
	ds_read_b64_tr_b16 v[190:191], v153 offset:14400
	ds_read_b64_tr_b16 v[192:193], v153 offset:16960
	s_waitcnt lgkmcnt(6)
	v_mfma_f32_32x32x16_bf16 v[18:33], v[82:85], v[214:217], v[18:33]
	v_exp_f32_e32 v95, v95
	v_exp_f32_e32 v96, v96
	v_exp_f32_e32 v97, v97
	v_add_f32_e32 v238, v238, v90
	ds_read_b64_tr_b16 v[214:215], v153 offset:14464
	ds_read_b64_tr_b16 v[216:217], v153 offset:17024
	s_waitcnt lgkmcnt(6)
	v_mfma_f32_32x32x16_bf16 v[34:49], v[82:85], v[234:237], v[34:49]
	v_add_f32_e32 v239, v239, v91
	v_add_f32_e32 v238, v238, v92
	v_add_f32_e32 v239, v239, v93
	v_cvt_pk_bf16_f32 v90, v90, v91
	v_cvt_pk_bf16_f32 v91, v92, v93
	v_cvt_pk_bf16_f32 v92, v94, v95
	v_cvt_pk_bf16_f32 v93, v96, v97
	ds_read_b64_tr_b16 v[234:235], v153 offset:14528
	ds_read_b64_tr_b16 v[236:237], v153 offset:17088
	s_waitcnt lgkmcnt(6)
	v_mfma_f32_32x32x16_bf16 v[2:17], v[90:93], v[154:157], v[2:17]
	v_add_f32_e32 v238, v238, v94
	v_add_f32_e32 v239, v239, v95
	v_add_f32_e32 v238, v238, v96
	v_add_f32_e32 v239, v239, v97
	v_exp_f32_e32 v98, v98
	v_exp_f32_e32 v99, v99
	ds_read_b64_tr_b16 v[154:155], v153 offset:19456
	ds_read_b64_tr_b16 v[156:157], v153 offset:22016
	s_waitcnt lgkmcnt(6)
	v_mfma_f32_32x32x16_bf16 v[50:65], v[90:93], v[190:193], v[50:65]
	v_exp_f32_e32 v100, v100
	v_exp_f32_e32 v101, v101
	v_exp_f32_e32 v102, v102
	ds_read_b64_tr_b16 v[190:191], v153 offset:19520
	ds_read_b64_tr_b16 v[192:193], v153 offset:22080
	s_waitcnt lgkmcnt(6)
	v_mfma_f32_32x32x16_bf16 v[18:33], v[90:93], v[214:217], v[18:33]
	v_exp_f32_e32 v103, v103
	v_exp_f32_e32 v104, v104
	v_exp_f32_e32 v105, v105
	v_add_f32_e32 v238, v238, v98
	ds_read_b64_tr_b16 v[214:215], v153 offset:19584
	ds_read_b64_tr_b16 v[216:217], v153 offset:22144
	s_waitcnt lgkmcnt(6)
	v_mfma_f32_32x32x16_bf16 v[34:49], v[90:93], v[234:237], v[34:49]
	v_add_f32_e32 v239, v239, v99
	v_add_f32_e32 v238, v238, v100
	v_add_f32_e32 v239, v239, v101
	v_cvt_pk_bf16_f32 v98, v98, v99
	v_cvt_pk_bf16_f32 v99, v100, v101
	v_cvt_pk_bf16_f32 v100, v102, v103
	v_cvt_pk_bf16_f32 v101, v104, v105
	ds_read_b64_tr_b16 v[234:235], v153 offset:19648
	ds_read_b64_tr_b16 v[236:237], v153 offset:22208
	s_waitcnt lgkmcnt(6)
	v_mfma_f32_32x32x16_bf16 v[2:17], v[98:101], v[154:157], v[2:17]
	v_add_f32_e32 v238, v238, v102
	v_add_f32_e32 v239, v239, v103
	v_add_f32_e32 v238, v238, v104
	v_add_f32_e32 v239, v239, v105
	v_exp_f32_e32 v106, v106
	v_exp_f32_e32 v107, v107
	ds_read_b64_tr_b16 v[154:155], v153 offset:24576
	ds_read_b64_tr_b16 v[156:157], v153 offset:27136
	s_waitcnt lgkmcnt(6)
	v_mfma_f32_32x32x16_bf16 v[50:65], v[98:101], v[190:193], v[50:65]
	v_exp_f32_e32 v108, v108
	v_exp_f32_e32 v109, v109
	v_exp_f32_e32 v110, v110
	ds_read_b64_tr_b16 v[190:191], v153 offset:24640
	ds_read_b64_tr_b16 v[192:193], v153 offset:27200
	s_waitcnt lgkmcnt(6)
	v_mfma_f32_32x32x16_bf16 v[18:33], v[98:101], v[214:217], v[18:33]
	v_exp_f32_e32 v111, v111
	v_exp_f32_e32 v112, v112
	v_exp_f32_e32 v113, v113
	v_add_f32_e32 v238, v238, v106
	ds_read_b64_tr_b16 v[214:215], v153 offset:24704
	ds_read_b64_tr_b16 v[216:217], v153 offset:27264
	s_waitcnt lgkmcnt(6)
	v_mfma_f32_32x32x16_bf16 v[34:49], v[98:101], v[234:237], v[34:49]
	v_add_f32_e32 v239, v239, v107
	v_add_f32_e32 v238, v238, v108
	v_add_f32_e32 v239, v239, v109
	v_cvt_pk_bf16_f32 v106, v106, v107
	v_cvt_pk_bf16_f32 v107, v108, v109
	v_cvt_pk_bf16_f32 v108, v110, v111
	v_cvt_pk_bf16_f32 v109, v112, v113
	ds_read_b64_tr_b16 v[234:235], v153 offset:24768
	ds_read_b64_tr_b16 v[236:237], v153 offset:27328
	s_waitcnt lgkmcnt(6)
	v_mfma_f32_32x32x16_bf16 v[2:17], v[106:109], v[154:157], v[2:17]
	v_add_f32_e32 v238, v238, v110
	v_add_f32_e32 v239, v239, v111
	v_add_f32_e32 v238, v238, v112
	v_add_f32_e32 v239, v239, v113
	v_add_f32_e32 v238, v238, v239
	s_waitcnt lgkmcnt(4)
	v_mfma_f32_32x32x16_bf16 v[50:65], v[106:109], v[190:193], v[50:65]
	s_waitcnt lgkmcnt(2)
	v_mfma_f32_32x32x16_bf16 v[18:33], v[106:109], v[214:217], v[18:33]
	s_waitcnt lgkmcnt(0)
	v_mfma_f32_32x32x16_bf16 v[34:49], v[106:109], v[234:237], v[34:49]
	s_setprio 0
	s_movk_i32 s77, 0x110

.LBB0_74:
.LBB0_75:
	v_add3_u32 v190, s26, v182, v181
	ds_read_b64_tr_b16 v[214:215], v190 offset:9216
	ds_read_b64_tr_b16 v[216:217], v190 offset:11776
	ds_read_b64_tr_b16 v[244:245], v190 offset:9280
	ds_read_b64_tr_b16 v[246:247], v190 offset:11840
	ds_read_b64_tr_b16 v[206:207], v190 offset:9344
	ds_read_b64_tr_b16 v[208:209], v190 offset:11904
	v_exp_f32_e32 v82, v82
	v_exp_f32_e32 v83, v83
	v_exp_f32_e32 v84, v84
	v_exp_f32_e32 v85, v85
	v_exp_f32_e32 v86, v86
	v_exp_f32_e32 v87, v87
	v_exp_f32_e32 v88, v88
	v_exp_f32_e32 v89, v89
	v_add_f32_e32 v242, v82, v83
	v_add_f32_e32 v243, v243, v84
	v_add_f32_e32 v242, v242, v85
	v_cvt_pk_bf16_f32 v82, v82, v83
	v_cvt_pk_bf16_f32 v83, v84, v85
	v_cvt_pk_bf16_f32 v84, v86, v87
	v_cvt_pk_bf16_f32 v85, v88, v89
	s_setprio 1
	s_waitcnt lgkmcnt(4)
	v_mfma_f32_32x32x16_bf16 v[2:17], v[82:85], v[214:217], v[2:17]
	v_add_f32_e32 v243, v243, v86
	v_add_f32_e32 v242, v242, v87
	v_add_f32_e32 v243, v243, v88
	v_add_f32_e32 v242, v242, v89
	v_exp_f32_e32 v90, v90
	v_exp_f32_e32 v91, v91
	ds_read_b64_tr_b16 v[214:215], v190 offset:9408
	ds_read_b64_tr_b16 v[216:217], v190 offset:11968
	s_waitcnt lgkmcnt(4)
	v_mfma_f32_32x32x16_bf16 v[50:65], v[82:85], v[244:247], v[50:65]
	v_exp_f32_e32 v92, v92
	v_exp_f32_e32 v93, v93
	v_exp_f32_e32 v94, v94
	ds_read_b64_tr_b16 v[244:245], v190 offset:14336
	ds_read_b64_tr_b16 v[246:247], v190 offset:16896
	s_waitcnt lgkmcnt(4)
	v_mfma_f32_32x32x16_bf16 v[34:49], v[82:85], v[206:209], v[34:49]
	v_exp_f32_e32 v95, v95
	v_exp_f32_e32 v96, v96
	v_exp_f32_e32 v97, v97
	v_add_f32_e32 v243, v243, v90
	ds_read_b64_tr_b16 v[206:207], v190 offset:14400
	ds_read_b64_tr_b16 v[208:209], v190 offset:16960
	s_waitcnt lgkmcnt(4)
	v_mfma_f32_32x32x16_bf16 v[18:33], v[82:85], v[214:217], v[18:33]
	v_add_f32_e32 v242, v242, v91
	v_add_f32_e32 v243, v243, v92
	v_add_f32_e32 v242, v242, v93
	v_cvt_pk_bf16_f32 v90, v90, v91
	v_cvt_pk_bf16_f32 v91, v92, v93
	v_cvt_pk_bf16_f32 v92, v94, v95
	v_cvt_pk_bf16_f32 v93, v96, v97
	ds_read_b64_tr_b16 v[214:215], v190 offset:14464
	ds_read_b64_tr_b16 v[216:217], v190 offset:17024
	s_waitcnt lgkmcnt(4)
	v_mfma_f32_32x32x16_bf16 v[2:17], v[90:93], v[244:247], v[2:17]
	v_add_f32_e32 v243, v243, v94
	v_add_f32_e32 v242, v242, v95
	v_add_f32_e32 v243, v243, v96
	v_add_f32_e32 v242, v242, v97
	v_exp_f32_e32 v98, v98
	v_exp_f32_e32 v99, v99
	ds_read_b64_tr_b16 v[244:245], v190 offset:14528
	ds_read_b64_tr_b16 v[246:247], v190 offset:17088
	s_waitcnt lgkmcnt(4)
	v_mfma_f32_32x32x16_bf16 v[50:65], v[90:93], v[206:209], v[50:65]
	v_exp_f32_e32 v100, v100
	v_exp_f32_e32 v101, v101
	v_exp_f32_e32 v102, v102
	ds_read_b64_tr_b16 v[206:207], v190 offset:19456
	ds_read_b64_tr_b16 v[208:209], v190 offset:22016
	s_waitcnt lgkmcnt(4)
	v_mfma_f32_32x32x16_bf16 v[34:49], v[90:93], v[214:217], v[34:49]
	v_exp_f32_e32 v103, v103
	v_exp_f32_e32 v104, v104
	v_exp_f32_e32 v105, v105
	v_add_f32_e32 v243, v243, v98
	ds_read_b64_tr_b16 v[214:215], v190 offset:19520
	ds_read_b64_tr_b16 v[216:217], v190 offset:22080
	s_waitcnt lgkmcnt(4)
	v_mfma_f32_32x32x16_bf16 v[18:33], v[90:93], v[244:247], v[18:33]
	v_add_f32_e32 v242, v242, v99
	v_add_f32_e32 v243, v243, v100
	v_add_f32_e32 v242, v242, v101
	v_cvt_pk_bf16_f32 v98, v98, v99
	v_cvt_pk_bf16_f32 v99, v100, v101
	v_cvt_pk_bf16_f32 v100, v102, v103
	v_cvt_pk_bf16_f32 v101, v104, v105
	ds_read_b64_tr_b16 v[244:245], v190 offset:19584
	ds_read_b64_tr_b16 v[246:247], v190 offset:22144
	s_waitcnt lgkmcnt(4)
	v_mfma_f32_32x32x16_bf16 v[2:17], v[98:101], v[206:209], v[2:17]
	v_add_f32_e32 v243, v243, v102
	v_add_f32_e32 v242, v242, v103
	v_add_f32_e32 v243, v243, v104
	v_add_f32_e32 v242, v242, v105
	v_exp_f32_e32 v106, v106
	v_exp_f32_e32 v107, v107
	ds_read_b64_tr_b16 v[206:207], v190 offset:19648
	ds_read_b64_tr_b16 v[208:209], v190 offset:22208
	s_waitcnt lgkmcnt(4)
	v_mfma_f32_32x32x16_bf16 v[50:65], v[98:101], v[214:217], v[50:65]
	v_exp_f32_e32 v108, v108
	v_exp_f32_e32 v109, v109
	v_exp_f32_e32 v110, v110
	ds_read_b64_tr_b16 v[214:215], v190 offset:24576
	ds_read_b64_tr_b16 v[216:217], v190 offset:27136
	s_waitcnt lgkmcnt(4)
	v_mfma_f32_32x32x16_bf16 v[34:49], v[98:101], v[244:247], v[34:49]
	v_exp_f32_e32 v111, v111
	v_exp_f32_e32 v112, v112
	v_exp_f32_e32 v113, v113
	v_add_f32_e32 v243, v243, v106
	ds_read_b64_tr_b16 v[244:245], v190 offset:24640
	ds_read_b64_tr_b16 v[246:247], v190 offset:27200
	s_waitcnt lgkmcnt(4)
	v_mfma_f32_32x32x16_bf16 v[18:33], v[98:101], v[206:209], v[18:33]
	v_add_f32_e32 v242, v242, v107
	v_add_f32_e32 v243, v243, v108
	v_add_f32_e32 v242, v242, v109
	v_cvt_pk_bf16_f32 v106, v106, v107
	v_cvt_pk_bf16_f32 v107, v108, v109
	v_cvt_pk_bf16_f32 v108, v110, v111
	v_cvt_pk_bf16_f32 v109, v112, v113
	ds_read_b64_tr_b16 v[206:207], v190 offset:24704
	ds_read_b64_tr_b16 v[208:209], v190 offset:27264
	s_waitcnt lgkmcnt(4)
	v_mfma_f32_32x32x16_bf16 v[2:17], v[106:109], v[214:217], v[2:17]
	v_add_f32_e32 v243, v243, v110
	v_add_f32_e32 v242, v242, v111
	v_add_f32_e32 v243, v243, v112
	v_add_f32_e32 v242, v242, v113
	v_add_f32_e32 v243, v243, v242
	ds_read_b64_tr_b16 v[214:215], v190 offset:24768
	ds_read_b64_tr_b16 v[216:217], v190 offset:27328
	s_waitcnt lgkmcnt(4)
	v_mfma_f32_32x32x16_bf16 v[50:65], v[106:109], v[244:247], v[50:65]
	s_waitcnt lgkmcnt(2)
	v_mfma_f32_32x32x16_bf16 v[34:49], v[106:109], v[206:209], v[34:49]
	s_waitcnt lgkmcnt(0)
	v_mfma_f32_32x32x16_bf16 v[18:33], v[106:109], v[214:217], v[18:33]
	s_setprio 0
	s_movk_i32 s77, 0x110

.LBB0_89:
.LBB0_90:
	v_add3_u32 v153, s26, v182, v181
	ds_read_b64_tr_b16 v[154:155], v153 offset:9216
	ds_read_b64_tr_b16 v[156:157], v153 offset:11776
	ds_read_b64_tr_b16 v[162:163], v153 offset:9280
	ds_read_b64_tr_b16 v[164:165], v153 offset:11840
	ds_read_b64_tr_b16 v[190:191], v153 offset:9344
	ds_read_b64_tr_b16 v[192:193], v153 offset:11904
	ds_read_b64_tr_b16 v[206:207], v153 offset:9408
	ds_read_b64_tr_b16 v[208:209], v153 offset:11968
	v_exp_f32_e32 v82, v82
	v_exp_f32_e32 v83, v83
	v_exp_f32_e32 v84, v84
	v_exp_f32_e32 v85, v85
	v_exp_f32_e32 v86, v86
	v_exp_f32_e32 v87, v87
	v_exp_f32_e32 v88, v88
	v_exp_f32_e32 v89, v89
	v_add_f32_e32 v239, v82, v83
	v_add_f32_e32 v238, v238, v84
	v_add_f32_e32 v239, v239, v85
	v_cvt_pk_bf16_f32 v82, v82, v83
	v_cvt_pk_bf16_f32 v83, v84, v85
	v_cvt_pk_bf16_f32 v84, v86, v87
	v_cvt_pk_bf16_f32 v85, v88, v89
	s_setprio 1
	s_waitcnt lgkmcnt(6)
	v_mfma_f32_32x32x16_bf16 v[2:17], v[82:85], v[154:157], v[2:17]
	v_add_f32_e32 v238, v238, v86
	v_add_f32_e32 v239, v239, v87
	v_add_f32_e32 v238, v238, v88
	v_add_f32_e32 v239, v239, v89
	v_exp_f32_e32 v90, v90
	v_exp_f32_e32 v91, v91
	ds_read_b64_tr_b16 v[154:155], v153 offset:14336
	ds_read_b64_tr_b16 v[156:157], v153 offset:16896
	s_waitcnt lgkmcnt(6)
	v_mfma_f32_32x32x16_bf16 v[50:65], v[82:85], v[162:165], v[50:65]
	v_exp_f32_e32 v92, v92
	v_exp_f32_e32 v93, v93
	v_exp_f32_e32 v94, v94
	ds_read_b64_tr_b16 v[162:163], v153 offset:14400
	ds_read_b64_tr_b16 v[164:165], v153 offset:16960
	s_waitcnt lgkmcnt(6)
	v_mfma_f32_32x32x16_bf16 v[18:33], v[82:85], v[190:193], v[18:33]
	v_exp_f32_e32 v95, v95
	v_exp_f32_e32 v96, v96
	v_exp_f32_e32 v97, v97
	v_add_f32_e32 v238, v238, v90
	ds_read_b64_tr_b16 v[190:191], v153 offset:14464
	ds_read_b64_tr_b16 v[192:193], v153 offset:17024
	s_waitcnt lgkmcnt(6)
	v_mfma_f32_32x32x16_bf16 v[34:49], v[82:85], v[206:209], v[34:49]
	v_add_f32_e32 v239, v239, v91
	v_add_f32_e32 v238, v238, v92
	v_add_f32_e32 v239, v239, v93
	v_cvt_pk_bf16_f32 v90, v90, v91
	v_cvt_pk_bf16_f32 v91, v92, v93
	v_cvt_pk_bf16_f32 v92, v94, v95
	v_cvt_pk_bf16_f32 v93, v96, v97
	ds_read_b64_tr_b16 v[206:207], v153 offset:14528
	ds_read_b64_tr_b16 v[208:209], v153 offset:17088
	s_waitcnt lgkmcnt(6)
	v_mfma_f32_32x32x16_bf16 v[2:17], v[90:93], v[154:157], v[2:17]
	v_add_f32_e32 v238, v238, v94
	v_add_f32_e32 v239, v239, v95
	v_add_f32_e32 v238, v238, v96
	v_add_f32_e32 v239, v239, v97
	v_exp_f32_e32 v98, v98
	v_exp_f32_e32 v99, v99
	ds_read_b64_tr_b16 v[154:155], v153 offset:19456
	ds_read_b64_tr_b16 v[156:157], v153 offset:22016
	s_waitcnt lgkmcnt(6)
	v_mfma_f32_32x32x16_bf16 v[50:65], v[90:93], v[162:165], v[50:65]
	v_exp_f32_e32 v100, v100
	v_exp_f32_e32 v101, v101
	v_exp_f32_e32 v102, v102
	ds_read_b64_tr_b16 v[162:163], v153 offset:19520
	ds_read_b64_tr_b16 v[164:165], v153 offset:22080
	s_waitcnt lgkmcnt(6)
	v_mfma_f32_32x32x16_bf16 v[18:33], v[90:93], v[190:193], v[18:33]
	v_exp_f32_e32 v103, v103
	v_exp_f32_e32 v104, v104
	v_exp_f32_e32 v105, v105
	v_add_f32_e32 v238, v238, v98
	ds_read_b64_tr_b16 v[190:191], v153 offset:19584
	ds_read_b64_tr_b16 v[192:193], v153 offset:22144
	s_waitcnt lgkmcnt(6)
	v_mfma_f32_32x32x16_bf16 v[34:49], v[90:93], v[206:209], v[34:49]
	v_add_f32_e32 v239, v239, v99
	v_add_f32_e32 v238, v238, v100
	v_add_f32_e32 v239, v239, v101
	v_cvt_pk_bf16_f32 v98, v98, v99
	v_cvt_pk_bf16_f32 v99, v100, v101
	v_cvt_pk_bf16_f32 v100, v102, v103
	v_cvt_pk_bf16_f32 v101, v104, v105
	ds_read_b64_tr_b16 v[206:207], v153 offset:19648
	ds_read_b64_tr_b16 v[208:209], v153 offset:22208
	s_waitcnt lgkmcnt(6)
	v_mfma_f32_32x32x16_bf16 v[2:17], v[98:101], v[154:157], v[2:17]
	v_add_f32_e32 v238, v238, v102
	v_add_f32_e32 v239, v239, v103
	v_add_f32_e32 v238, v238, v104
	v_add_f32_e32 v239, v239, v105
	v_exp_f32_e32 v106, v106
	v_exp_f32_e32 v107, v107
	ds_read_b64_tr_b16 v[154:155], v153 offset:24576
	ds_read_b64_tr_b16 v[156:157], v153 offset:27136
	s_waitcnt lgkmcnt(6)
	v_mfma_f32_32x32x16_bf16 v[50:65], v[98:101], v[162:165], v[50:65]
	v_exp_f32_e32 v108, v108
	v_exp_f32_e32 v109, v109
	v_exp_f32_e32 v110, v110
	ds_read_b64_tr_b16 v[162:163], v153 offset:24640
	ds_read_b64_tr_b16 v[164:165], v153 offset:27200
	s_waitcnt lgkmcnt(6)
	v_mfma_f32_32x32x16_bf16 v[18:33], v[98:101], v[190:193], v[18:33]
	v_exp_f32_e32 v111, v111
	v_exp_f32_e32 v112, v112
	v_exp_f32_e32 v113, v113
	v_add_f32_e32 v238, v238, v106
	ds_read_b64_tr_b16 v[190:191], v153 offset:24704
	ds_read_b64_tr_b16 v[192:193], v153 offset:27264
	s_waitcnt lgkmcnt(6)
	v_mfma_f32_32x32x16_bf16 v[34:49], v[98:101], v[206:209], v[34:49]
	v_add_f32_e32 v239, v239, v107
	v_add_f32_e32 v238, v238, v108
	v_add_f32_e32 v239, v239, v109
	v_cvt_pk_bf16_f32 v106, v106, v107
	v_cvt_pk_bf16_f32 v107, v108, v109
	v_cvt_pk_bf16_f32 v108, v110, v111
	v_cvt_pk_bf16_f32 v109, v112, v113
	ds_read_b64_tr_b16 v[206:207], v153 offset:24768
	ds_read_b64_tr_b16 v[208:209], v153 offset:27328
	s_waitcnt lgkmcnt(6)
	v_mfma_f32_32x32x16_bf16 v[2:17], v[106:109], v[154:157], v[2:17]
	v_add_f32_e32 v238, v238, v110
	v_add_f32_e32 v239, v239, v111
	v_add_f32_e32 v238, v238, v112
	v_add_f32_e32 v239, v239, v113
	v_add_f32_e32 v238, v238, v239
	s_waitcnt lgkmcnt(4)
	v_mfma_f32_32x32x16_bf16 v[50:65], v[106:109], v[162:165], v[50:65]
	s_waitcnt lgkmcnt(2)
	v_mfma_f32_32x32x16_bf16 v[18:33], v[106:109], v[190:193], v[18:33]
	s_waitcnt lgkmcnt(0)
	v_mfma_f32_32x32x16_bf16 v[34:49], v[106:109], v[206:209], v[34:49]
	s_setprio 0
	s_movk_i32 s77, 0x110
